# ssd_out staging hand-written (12 loads in flight); mlstm_local K/V staging loads up front and batched column-sum reads
# speedup vs baseline: 1.0106x; 1.0027x over previous
.LBB0_205:
	s_or_b64 exec, exec, s[28:29]
	v_lshlrev_b32_e32 v0, 4, v8
	v_and_b32_e32 v168, 0x1f0, v0
	v_ashrrev_i32_e32 v9, 5, v8
	v_mov_b64_e32 v[0:1], s[14:15]
	v_mad_i64_i32 v[2:3], s[4:5], v9, s54, v[0:1]
	s_lshl_b32 s30, s70, 9
	v_lshl_add_u64 v[2:3], v[2:3], 0, s[30:31]
	v_lshl_add_u64 v[6:7], v[2:3], 0, v[168:169]
	v_add_co_u32_e32 v252, vcc, 0x1000, v6
	s_nop 1
	v_addc_co_u32_e32 v253, vcc, 0, v7, vcc
	global_load_dwordx4 v[24:27], v[252:253], off offset:-2048
	global_load_dwordx4 v[28:31], v[252:253], off
	v_add_co_u32_e32 v252, vcc, 0x36000, v252
	s_nop 1
	v_addc_co_u32_e32 v253, vcc, 0, v253, vcc
	global_load_dwordx4 v[32:35], v[252:253], off offset:-2048
	global_load_dwordx4 v[36:39], v[252:253], off
	v_add_co_u32_e32 v252, vcc, 0x36000, v252
	s_nop 1
	v_addc_co_u32_e32 v253, vcc, 0, v253, vcc
	global_load_dwordx4 v[40:43], v[252:253], off offset:-2048
	global_load_dwordx4 v[44:47], v[252:253], off
	v_add_co_u32_e32 v252, vcc, 0x36000, v252
	s_nop 1
	v_addc_co_u32_e32 v253, vcc, 0, v253, vcc
	global_load_dwordx4 v[48:51], v[252:253], off offset:-2048
	global_load_dwordx4 v[52:55], v[252:253], off
	s_waitcnt lgkmcnt(0)
	s_barrier
	s_waitcnt vmcnt(7)
	v_mov_b32_e32 v2, v24
	v_mov_b32_e32 v3, v25
	v_mov_b32_e32 v4, v26
	v_mov_b32_e32 v5, v27
	v_add_co_u32_e32 v6, vcc, s63, v6
	v_add_u32_e32 v10, 0, v168
	s_nop 0
	v_addc_co_u32_e32 v7, vcc, 0, v7, vcc
	v_lshl_add_u32 v6, v9, 2, 0
	ds_read_b32 v6, v6
	v_lshlrev_b32_e32 v16, 16, v2
	v_and_b32_e32 v17, 0xffff0000, v2
	v_lshlrev_b32_e32 v18, 16, v3
	v_and_b32_e32 v19, 0xffff0000, v3
	v_lshlrev_b32_e32 v20, 16, v4
	v_and_b32_e32 v21, 0xffff0000, v4
	v_lshlrev_b32_e32 v22, 16, v5
	v_and_b32_e32 v23, 0xffff0000, v5
	s_waitcnt lgkmcnt(0)
	v_pk_mul_f32 v[2:3], v[6:7], v[16:17] op_sel_hi:[0,1]
	v_pk_mul_f32 v[4:5], v[6:7], v[18:19] op_sel_hi:[0,1]
	v_cvt_pk_bf16_f32 v2, v2, v3
	v_cvt_pk_bf16_f32 v3, v4, v5
	v_pk_mul_f32 v[4:5], v[6:7], v[20:21] op_sel_hi:[0,1]
	v_pk_mul_f32 v[6:7], v[6:7], v[22:23] op_sel_hi:[0,1]
	v_cvt_pk_bf16_f32 v4, v4, v5
	v_cvt_pk_bf16_f32 v5, v6, v7
	v_mad_u64_u32 v[6:7], s[4:5], v9, s64, v[10:11]
	ds_write_b128 v6, v[2:5] offset:1024
	s_waitcnt vmcnt(6)
	ds_write_b128 v6, v[28:31] offset:35840
	v_add_u32_e32 v2, 0x200, v8
	v_ashrrev_i32_e32 v9, 5, v2
	v_mad_i64_i32 v[2:3], s[4:5], v9, s54, v[0:1]
	v_lshl_add_u64 v[2:3], v[2:3], 0, s[30:31]
	v_lshl_add_u64 v[6:7], v[2:3], 0, v[168:169]
	s_waitcnt vmcnt(5)
	v_mov_b32_e32 v2, v32
	v_mov_b32_e32 v3, v33
	v_mov_b32_e32 v4, v34
	v_mov_b32_e32 v5, v35
	v_add_co_u32_e32 v6, vcc, s63, v6
	v_lshlrev_b32_e32 v16, 16, v2
	v_addc_co_u32_e32 v7, vcc, 0, v7, vcc
	v_lshl_add_u32 v6, v9, 2, 0
	ds_read_b32 v6, v6
	v_and_b32_e32 v17, 0xffff0000, v2
	v_lshlrev_b32_e32 v18, 16, v3
	v_and_b32_e32 v19, 0xffff0000, v3
	v_lshlrev_b32_e32 v20, 16, v4
	v_and_b32_e32 v21, 0xffff0000, v4
	v_lshlrev_b32_e32 v22, 16, v5
	v_and_b32_e32 v23, 0xffff0000, v5
	s_waitcnt lgkmcnt(0)
	v_pk_mul_f32 v[2:3], v[6:7], v[16:17] op_sel_hi:[0,1]
	v_pk_mul_f32 v[4:5], v[6:7], v[18:19] op_sel_hi:[0,1]
	v_cvt_pk_bf16_f32 v2, v2, v3
	v_cvt_pk_bf16_f32 v3, v4, v5
	v_pk_mul_f32 v[4:5], v[6:7], v[20:21] op_sel_hi:[0,1]
	v_pk_mul_f32 v[6:7], v[6:7], v[22:23] op_sel_hi:[0,1]
	v_cvt_pk_bf16_f32 v4, v4, v5
	v_cvt_pk_bf16_f32 v5, v6, v7
	v_mad_u64_u32 v[6:7], s[4:5], v9, s64, v[10:11]
	ds_write_b128 v6, v[2:5] offset:1024
	s_waitcnt vmcnt(4)
	ds_write_b128 v6, v[36:39] offset:35840
	v_add_u32_e32 v2, 0x400, v8
	v_ashrrev_i32_e32 v9, 5, v2
	v_mad_i64_i32 v[2:3], s[4:5], v9, s54, v[0:1]
	v_lshl_add_u64 v[2:3], v[2:3], 0, s[30:31]
	v_lshl_add_u64 v[6:7], v[2:3], 0, v[168:169]
	s_waitcnt vmcnt(3)
	v_mov_b32_e32 v2, v40
	v_mov_b32_e32 v3, v41
	v_mov_b32_e32 v4, v42
	v_mov_b32_e32 v5, v43
	v_add_co_u32_e32 v6, vcc, s63, v6
	v_lshlrev_b32_e32 v16, 16, v2
	v_addc_co_u32_e32 v7, vcc, 0, v7, vcc
	v_lshl_add_u32 v6, v9, 2, 0
	ds_read_b32 v6, v6
	v_and_b32_e32 v17, 0xffff0000, v2
	v_lshlrev_b32_e32 v18, 16, v3
	v_and_b32_e32 v19, 0xffff0000, v3
	v_lshlrev_b32_e32 v20, 16, v4
	v_and_b32_e32 v21, 0xffff0000, v4
	v_lshlrev_b32_e32 v22, 16, v5
	v_and_b32_e32 v23, 0xffff0000, v5
	s_waitcnt lgkmcnt(0)
	v_pk_mul_f32 v[2:3], v[6:7], v[16:17] op_sel_hi:[0,1]
	v_pk_mul_f32 v[4:5], v[6:7], v[18:19] op_sel_hi:[0,1]
	v_cvt_pk_bf16_f32 v2, v2, v3
	v_cvt_pk_bf16_f32 v3, v4, v5
	v_pk_mul_f32 v[4:5], v[6:7], v[20:21] op_sel_hi:[0,1]
	v_pk_mul_f32 v[6:7], v[6:7], v[22:23] op_sel_hi:[0,1]
	v_cvt_pk_bf16_f32 v4, v4, v5
	v_cvt_pk_bf16_f32 v5, v6, v7
	v_mad_u64_u32 v[6:7], s[4:5], v9, s64, v[10:11]
	ds_write_b128 v6, v[2:5] offset:1024
	s_waitcnt vmcnt(2)
	ds_write_b128 v6, v[44:47] offset:35840
	v_add_u32_e32 v2, 0x600, v8
	v_ashrrev_i32_e32 v9, 5, v2
	v_mad_i64_i32 v[0:1], s[4:5], v9, s54, v[0:1]
	v_lshl_add_u64 v[0:1], v[0:1], 0, s[30:31]
	v_lshl_add_u64 v[4:5], v[0:1], 0, v[168:169]
	s_waitcnt vmcnt(1)
	v_mov_b32_e32 v0, v48
	v_mov_b32_e32 v1, v49
	v_mov_b32_e32 v2, v50
	v_mov_b32_e32 v3, v51
	v_add_co_u32_e32 v4, vcc, s63, v4
	v_lshl_add_u32 v12, v9, 2, 0
	s_nop 0
	v_addc_co_u32_e32 v5, vcc, 0, v5, vcc
	ds_read_b32 v12, v12
	v_lshlrev_b32_e32 v14, 16, v0
	v_and_b32_e32 v15, 0xffff0000, v0
	v_lshlrev_b32_e32 v16, 16, v1
	v_and_b32_e32 v17, 0xffff0000, v1
	v_lshlrev_b32_e32 v18, 16, v2
	v_and_b32_e32 v19, 0xffff0000, v2
	v_lshlrev_b32_e32 v20, 16, v3
	v_and_b32_e32 v21, 0xffff0000, v3
	s_waitcnt lgkmcnt(0)
	v_pk_mul_f32 v[0:1], v[12:13], v[14:15] op_sel_hi:[0,1]
	v_pk_mul_f32 v[2:3], v[12:13], v[16:17] op_sel_hi:[0,1]
	v_cvt_pk_bf16_f32 v0, v0, v1
	v_cvt_pk_bf16_f32 v1, v2, v3
	v_pk_mul_f32 v[2:3], v[12:13], v[18:19] op_sel_hi:[0,1]
	v_pk_mul_f32 v[12:13], v[12:13], v[20:21] op_sel_hi:[0,1]
	v_cvt_pk_bf16_f32 v2, v2, v3
	v_cvt_pk_bf16_f32 v3, v12, v13
	v_mad_u64_u32 v[12:13], s[4:5], v9, s64, v[10:11]
	s_movk_i32 s4, 0xff
	s_nop 0
	v_cmp_lt_i32_e32 vcc, s4, v8
	ds_write_b128 v12, v[0:3] offset:1024
	s_waitcnt vmcnt(0)
	ds_write_b128 v12, v[52:55] offset:35840
	s_waitcnt lgkmcnt(0)
	s_barrier
	s_and_saveexec_b64 s[4:5], vcc
	s_xor_b64 s[4:5], exec, s[4:5]
	s_ashr_i32 s15, s8, 31
	s_mov_b32 s14, s8
	s_or_saveexec_b64 s[4:5], s[4:5]
	v_mov_b64_e32 v[176:177], s[14:15]
	s_xor_b64 exec, exec, s[4:5]
	s_cbranch_execz .LBB0_201
	v_lshl_add_u32 v0, v8, 1, 0
	v_ashrrev_i32_e32 v9, 31, v8
	v_mov_b64_e32 v[176:177], s[8:9]
	ds_read_u16 v24, v0 offset:1024
	ds_read_u16 v25, v0 offset:1568
	ds_read_u16 v26, v0 offset:2112
	ds_read_u16 v27, v0 offset:2656
	ds_read_u16 v28, v0 offset:3200
	ds_read_u16 v29, v0 offset:3744
	ds_read_u16 v30, v0 offset:4288
	ds_read_u16 v31, v0 offset:4832
	ds_read_u16 v32, v0 offset:5376
	ds_read_u16 v33, v0 offset:5920
	ds_read_u16 v34, v0 offset:6464
	ds_read_u16 v35, v0 offset:7008
	ds_read_u16 v36, v0 offset:7552
	ds_read_u16 v37, v0 offset:8096
	ds_read_u16 v38, v0 offset:8640
	ds_read_u16 v39, v0 offset:9184
	s_waitcnt lgkmcnt(0)
	ds_read_u16 v40, v0 offset:9728
	ds_read_u16 v41, v0 offset:10272
	ds_read_u16 v42, v0 offset:10816
	ds_read_u16 v43, v0 offset:11360
	ds_read_u16 v44, v0 offset:11904
	ds_read_u16 v45, v0 offset:12448
	ds_read_u16 v46, v0 offset:12992
	ds_read_u16 v47, v0 offset:13536
	ds_read_u16 v48, v0 offset:14080
	ds_read_u16 v49, v0 offset:14624
	ds_read_u16 v50, v0 offset:15168
	ds_read_u16 v51, v0 offset:15712
	ds_read_u16 v52, v0 offset:16256
	ds_read_u16 v53, v0 offset:16800
	ds_read_u16 v54, v0 offset:17344
	ds_read_u16 v55, v0 offset:17888
	v_lshlrev_b32_e32 v24, 16, v24
	v_mov_b32_e32 v2, v24
	v_lshlrev_b32_e32 v25, 16, v25
	v_add_f32_e32 v2, v2, v25
	v_lshlrev_b32_e32 v26, 16, v26
	v_add_f32_e32 v2, v2, v26
	v_lshlrev_b32_e32 v27, 16, v27
	v_add_f32_e32 v2, v2, v27
	v_lshlrev_b32_e32 v28, 16, v28
	v_add_f32_e32 v2, v2, v28
	v_lshlrev_b32_e32 v29, 16, v29
	v_add_f32_e32 v2, v2, v29
	v_lshlrev_b32_e32 v30, 16, v30
	v_add_f32_e32 v2, v2, v30
	v_lshlrev_b32_e32 v31, 16, v31
	v_add_f32_e32 v2, v2, v31
	v_lshlrev_b32_e32 v32, 16, v32
	v_add_f32_e32 v2, v2, v32
	v_lshlrev_b32_e32 v33, 16, v33
	v_add_f32_e32 v2, v2, v33
	v_lshlrev_b32_e32 v34, 16, v34
	v_add_f32_e32 v2, v2, v34
	v_lshlrev_b32_e32 v35, 16, v35
	v_add_f32_e32 v2, v2, v35
	v_lshlrev_b32_e32 v36, 16, v36
	v_add_f32_e32 v2, v2, v36
	v_lshlrev_b32_e32 v37, 16, v37
	v_add_f32_e32 v2, v2, v37
	v_lshlrev_b32_e32 v38, 16, v38
	v_add_f32_e32 v2, v2, v38
	v_lshlrev_b32_e32 v39, 16, v39
	v_add_f32_e32 v2, v2, v39
	s_waitcnt lgkmcnt(0)
	ds_read_u16 v24, v0 offset:18432
	ds_read_u16 v25, v0 offset:18976
	ds_read_u16 v26, v0 offset:19520
	ds_read_u16 v27, v0 offset:20064
	ds_read_u16 v28, v0 offset:20608
	ds_read_u16 v29, v0 offset:21152
	ds_read_u16 v30, v0 offset:21696
	ds_read_u16 v31, v0 offset:22240
	ds_read_u16 v32, v0 offset:22784
	ds_read_u16 v33, v0 offset:23328
	ds_read_u16 v34, v0 offset:23872
	ds_read_u16 v35, v0 offset:24416
	ds_read_u16 v36, v0 offset:24960
	ds_read_u16 v37, v0 offset:25504
	ds_read_u16 v38, v0 offset:26048
	ds_read_u16 v39, v0 offset:26592
	v_lshlrev_b32_e32 v40, 16, v40
	v_add_f32_e32 v2, v2, v40
	v_lshlrev_b32_e32 v41, 16, v41
	v_add_f32_e32 v2, v2, v41
	v_lshlrev_b32_e32 v42, 16, v42
	v_add_f32_e32 v2, v2, v42
	v_lshlrev_b32_e32 v43, 16, v43
	v_add_f32_e32 v2, v2, v43
	v_lshlrev_b32_e32 v44, 16, v44
	v_add_f32_e32 v2, v2, v44
	v_lshlrev_b32_e32 v45, 16, v45
	v_add_f32_e32 v2, v2, v45
	v_lshlrev_b32_e32 v46, 16, v46
	v_add_f32_e32 v2, v2, v46
	v_lshlrev_b32_e32 v47, 16, v47
	v_add_f32_e32 v2, v2, v47
	v_lshlrev_b32_e32 v48, 16, v48
	v_add_f32_e32 v2, v2, v48
	v_lshlrev_b32_e32 v49, 16, v49
	v_add_f32_e32 v2, v2, v49
	v_lshlrev_b32_e32 v50, 16, v50
	v_add_f32_e32 v2, v2, v50
	v_lshlrev_b32_e32 v51, 16, v51
	v_add_f32_e32 v2, v2, v51
	v_lshlrev_b32_e32 v52, 16, v52
	v_add_f32_e32 v2, v2, v52
	v_lshlrev_b32_e32 v53, 16, v53
	v_add_f32_e32 v2, v2, v53
	v_lshlrev_b32_e32 v54, 16, v54
	v_add_f32_e32 v2, v2, v54
	v_lshlrev_b32_e32 v55, 16, v55
	v_add_f32_e32 v2, v2, v55
	s_waitcnt lgkmcnt(0)
	ds_read_u16 v40, v0 offset:27136
	ds_read_u16 v41, v0 offset:27680
	ds_read_u16 v42, v0 offset:28224
	ds_read_u16 v43, v0 offset:28768
	ds_read_u16 v44, v0 offset:29312
	ds_read_u16 v45, v0 offset:29856
	ds_read_u16 v46, v0 offset:30400
	ds_read_u16 v47, v0 offset:30944
	ds_read_u16 v48, v0 offset:31488
	ds_read_u16 v49, v0 offset:32032
	ds_read_u16 v50, v0 offset:32576
	ds_read_u16 v51, v0 offset:33120
	ds_read_u16 v52, v0 offset:33664
	ds_read_u16 v53, v0 offset:34208
	ds_read_u16 v54, v0 offset:34752
	ds_read_u16 v55, v0 offset:35296
	v_lshlrev_b32_e32 v24, 16, v24
	v_add_f32_e32 v2, v2, v24
	v_lshlrev_b32_e32 v25, 16, v25
	v_add_f32_e32 v2, v2, v25
	v_lshlrev_b32_e32 v26, 16, v26
	v_add_f32_e32 v2, v2, v26
	v_lshlrev_b32_e32 v27, 16, v27
	v_add_f32_e32 v2, v2, v27
	v_lshlrev_b32_e32 v28, 16, v28
	v_add_f32_e32 v2, v2, v28
	v_lshlrev_b32_e32 v29, 16, v29
	v_add_f32_e32 v2, v2, v29
	v_lshlrev_b32_e32 v30, 16, v30
	v_add_f32_e32 v2, v2, v30
	v_lshlrev_b32_e32 v31, 16, v31
	v_add_f32_e32 v2, v2, v31
	v_lshlrev_b32_e32 v32, 16, v32
	v_add_f32_e32 v2, v2, v32
	v_lshlrev_b32_e32 v33, 16, v33
	v_add_f32_e32 v2, v2, v33
	v_lshlrev_b32_e32 v34, 16, v34
	v_add_f32_e32 v2, v2, v34
	v_lshlrev_b32_e32 v35, 16, v35
	v_add_f32_e32 v2, v2, v35
	v_lshlrev_b32_e32 v36, 16, v36
	v_add_f32_e32 v2, v2, v36
	v_lshlrev_b32_e32 v37, 16, v37
	v_add_f32_e32 v2, v2, v37
	v_lshlrev_b32_e32 v38, 16, v38
	v_add_f32_e32 v2, v2, v38
	v_lshlrev_b32_e32 v39, 16, v39
	v_add_f32_e32 v2, v2, v39
	s_waitcnt lgkmcnt(0)
	v_lshlrev_b32_e32 v40, 16, v40
	v_add_f32_e32 v2, v2, v40
	v_lshlrev_b32_e32 v41, 16, v41
	v_add_f32_e32 v2, v2, v41
	v_lshlrev_b32_e32 v42, 16, v42
	v_add_f32_e32 v2, v2, v42
	v_lshlrev_b32_e32 v43, 16, v43
	v_add_f32_e32 v2, v2, v43
	v_lshlrev_b32_e32 v44, 16, v44
	v_add_f32_e32 v2, v2, v44
	v_lshlrev_b32_e32 v45, 16, v45
	v_add_f32_e32 v2, v2, v45
	v_lshlrev_b32_e32 v46, 16, v46
	v_add_f32_e32 v2, v2, v46
	v_lshlrev_b32_e32 v47, 16, v47
	v_add_f32_e32 v2, v2, v47
	v_lshlrev_b32_e32 v48, 16, v48
	v_add_f32_e32 v2, v2, v48
	v_lshlrev_b32_e32 v49, 16, v49
	v_add_f32_e32 v2, v2, v49
	v_lshlrev_b32_e32 v50, 16, v50
	v_add_f32_e32 v2, v2, v50
	v_lshlrev_b32_e32 v51, 16, v51
	v_add_f32_e32 v2, v2, v51
	v_lshlrev_b32_e32 v52, 16, v52
	v_add_f32_e32 v2, v2, v52
	v_lshlrev_b32_e32 v53, 16, v53
	v_add_f32_e32 v2, v2, v53
	v_lshlrev_b32_e32 v54, 16, v54
	v_add_f32_e32 v2, v2, v54
	v_lshlrev_b32_e32 v55, 16, v55
	v_add_f32_e32 v2, v2, v55
	v_lshl_add_u64 v[0:1], v[8:9], 2, s[6:7]
	global_store_dword v[0:1], v2, off
	s_branch .LBB0_201

.LBB0_650:
	s_ashr_i32 s30, s28, 6
	s_and_b32 s58, s28, 31
	s_lshl_b32 s2, s30, 11
	s_lshl_b32 s3, s58, 6
	v_mov_b32_e32 v142, v178
	s_or_b32 s29, s2, s3
	s_bfe_u32 s14, s28, 0x10005
	s_mul_i32 s3, s29, 0x3600
	v_and_b32_e32 v4, 63, v142
	v_ashrrev_i32_e32 v140, 6, v142
	s_mul_hi_i32 s2, s29, 0x3600
	s_add_u32 s8, s80, s3
	v_mul_u32_u24_e32 v0, 0x1b00, v4
	s_addc_u32 s9, s81, s2
	v_lshl_add_u32 v128, s14, 3, v140
	v_lshlrev_b32_e32 v168, 1, v0
	v_ashrrev_i32_e32 v129, 31, v128
	v_lshl_add_u64 v[0:1], s[8:9], 0, v[168:169]
	v_lshl_add_u64 v[0:1], v[128:129], 1, v[0:1]
	s_movk_i32 s2, 0x3000
	v_add_co_u32_e32 v0, vcc, s2, v0
	v_add_u32_e32 v138, s96, v128
	s_nop 0
	v_addc_co_u32_e32 v1, vcc, 0, v1, vcc
	global_load_ushort v0, v[0:1], off offset:1040
	v_ashrrev_i32_e32 v139, 31, v138
	v_readlane_b32 s36, v241, 11
	v_readlane_b32 s48, v241, 23
	v_readlane_b32 s49, v241, 24
	v_readlane_b32 s50, v241, 25
	v_readlane_b32 s51, v241, 26
	v_and_b32_e32 v141, 64, v188
	v_lshl_add_u32 v143, v142, 2, 0
	s_lshl_b32 s70, s14, 7
	s_add_i32 s71, s70, 0x280
	s_bitset1_b32 s70, 9
	v_readlane_b32 s37, v241, 12
	v_readlane_b32 s38, v241, 13
	v_readlane_b32 s39, v241, 14
	v_readlane_b32 s40, v241, 15
	v_readlane_b32 s41, v241, 16
	v_readlane_b32 s42, v241, 17
	v_readlane_b32 s43, v241, 18
	v_readlane_b32 s44, v241, 19
	v_readlane_b32 s45, v241, 20
	v_readlane_b32 s46, v241, 21
	v_readlane_b32 s47, v241, 22
	s_waitcnt vmcnt(0)
	v_lshlrev_b32_e32 v5, 16, v0
	v_lshlrev_b64 v[0:1], 2, v[138:139]
	v_lshl_add_u64 v[2:3], s[48:49], 0, v[0:1]
	global_load_dword v2, v[2:3], off
	v_lshl_add_u64 v[0:1], s[50:51], 0, v[0:1]
	global_load_dword v0, v[0:1], off
	s_waitcnt vmcnt(1)
	v_add_f32_e32 v2, v2, v5
	v_max_f32_e32 v3, 0, v2
	v_mul_f32_e64 v2, |v2|, s59
	v_exp_f32_e32 v2, v2
	s_waitcnt vmcnt(0)
	v_mul_f32_e32 v0, 0x3fb8aa3b, v0
	v_exp_f32_e32 v0, v0
	v_add_f32_e32 v2, 1.0, v2
	v_cmp_gt_f32_e32 vcc, s60, v2
	s_nop 1
	v_cndmask_b32_e64 v5, 0, 32, vcc
	v_ldexp_f32 v2, v2, v5
	v_log_f32_e32 v2, v2
	s_nop 0
	v_mul_f32_e32 v5, 0x3f317217, v2
	v_fma_f32 v5, v2, s61, -v5
	v_fmac_f32_e32 v5, 0x3377d1cf, v2
	v_fmac_f32_e32 v5, 0x3f317217, v2
	v_cmp_lt_f32_e64 s[2:3], |v2|, s62
	s_nop 1
	v_cndmask_b32_e64 v2, v2, v5, s[2:3]
	v_cndmask_b32_e32 v5, 0, v186, vcc
	v_sub_f32_e32 v2, v2, v5
	v_add_f32_e32 v2, v3, v2
	v_add_u32_e32 v3, -1, v188
	v_cmp_lt_i32_e32 vcc, v3, v141
	v_mul_f32_e64 v1, v2, -v0
	v_cmp_gt_u32_e64 s[2:3], 16, v4
	v_cndmask_b32_e32 v3, v3, v188, vcc
	v_lshlrev_b32_e32 v3, 2, v3
	ds_bpermute_b32 v3, v3, v1
	v_cmp_eq_u32_e32 vcc, 0, v4
	s_waitcnt lgkmcnt(0)
	v_fma_f32 v0, v2, -v0, v3
	v_cndmask_b32_e32 v0, v0, v1, vcc
	v_add_u32_e32 v1, -2, v188
	v_cmp_lt_i32_e32 vcc, v1, v141
	s_nop 1
	v_cndmask_b32_e32 v1, v1, v188, vcc
	v_lshlrev_b32_e32 v1, 2, v1
	ds_bpermute_b32 v1, v1, v0
	v_cmp_gt_u32_e32 vcc, 2, v4
	s_waitcnt lgkmcnt(0)
	v_add_f32_e32 v1, v0, v1
	v_cndmask_b32_e32 v0, v1, v0, vcc
	v_add_u32_e32 v1, -4, v188
	v_cmp_lt_i32_e32 vcc, v1, v141
	s_nop 1
	v_cndmask_b32_e32 v1, v1, v188, vcc
	v_lshlrev_b32_e32 v1, 2, v1
	ds_bpermute_b32 v1, v1, v0
	v_cmp_gt_u32_e32 vcc, 4, v4
	s_waitcnt lgkmcnt(0)
	v_add_f32_e32 v1, v0, v1
	v_cndmask_b32_e32 v0, v1, v0, vcc
	v_add_u32_e32 v1, -8, v188
	v_cmp_lt_i32_e32 vcc, v1, v141
	s_nop 1
	v_cndmask_b32_e32 v1, v1, v188, vcc
	v_lshlrev_b32_e32 v1, 2, v1
	ds_bpermute_b32 v1, v1, v0
	v_cmp_gt_u32_e32 vcc, 8, v4
	s_waitcnt lgkmcnt(0)
	v_add_f32_e32 v1, v0, v1
	v_cndmask_b32_e32 v0, v1, v0, vcc
	v_add_u32_e32 v1, -16, v188
	v_cmp_lt_i32_e32 vcc, v1, v141
	s_nop 1
	v_cndmask_b32_e32 v1, v1, v188, vcc
	v_lshlrev_b32_e32 v1, 2, v1
	ds_bpermute_b32 v1, v1, v0
	s_waitcnt lgkmcnt(0)
	v_add_f32_e32 v1, v0, v1
	v_cndmask_b32_e64 v0, v1, v0, s[2:3]
	v_subrev_u32_e32 v1, 32, v188
	v_cmp_lt_i32_e32 vcc, v1, v141
	s_nop 1
	v_cndmask_b32_e32 v1, v1, v188, vcc
	v_lshlrev_b32_e32 v1, 2, v1
	ds_bpermute_b32 v1, v1, v0
	v_cmp_gt_u32_e32 vcc, 32, v4
	s_waitcnt lgkmcnt(0)
	v_add_f32_e32 v1, v0, v1
	v_cndmask_b32_e32 v0, v1, v0, vcc
	v_add_u32_e32 v1, 0x1d400, v143
	ds_write_b32 v1, v0
	v_add_u32_e32 v0, 0x1dc00, v143
	ds_write_b32 v0, v2
	s_lshl_b32 s56, s14, 9
	s_mul_i32 s4, s14, 0x180
	s_sub_i32 s4, 0x200, s4
	v_mov_b32_e32 v8, s4
	s_mul_i32 s5, s29, 0xc00
	v_readlane_b32 s12, v240, 32
	s_mul_hi_i32 s4, s29, 0xc00
	s_add_u32 s12, s12, s5
	v_readlane_b32 s5, v240, 33
	s_addc_u32 s13, s5, s4
	v_mov_b32_e32 v9, v142
	v_mul_hi_i32 v10, v9, s67
	v_ashrrev_i32_e32 v10, 4, v10
	v_mul_lo_u32 v11, v10, s52
	v_sub_u32_e32 v11, v9, v11
	v_lshl_add_u32 v12, v11, 3, s56
	v_cmp_lt_u32_e32 vcc, 63, v11
	s_nop 1
	v_cndmask_b32_e64 v13, 0, 1, vcc
	v_mad_u32_u24 v12, v13, v8, v12
	v_mul_u32_u24_e32 v64, 0x420, v10
	v_lshl_add_u32 v64, v11, 4, v64
	v_mul_u32_u24_e32 v9, 0x110, v10
	v_lshl_add_u32 v9, v11, 4, v9
	v_add_u32_e32 v9, 0x10400, v9
	v_cndmask_b32_e32 v64, v64, v9, vcc
	v_cmp_lt_u32_e32 vcc, 79, v11
	v_add_u32_e32 v9, 0x4300, v9
	s_nop 0
	v_cndmask_b32_e64 v13, 0, 1, vcc
	v_cndmask_b32_e32 v64, v64, v9, vcc
	v_lshl_add_u32 v12, v13, 7, v12
	v_mul_u32_u24_e32 v9, 0xc00, v10
	v_lshl_add_u32 v9, v12, 1, v9
	global_load_dwordx4 v[16:19], v9, s[12:13]
	v_add_u32_e32 v9, 512, v142
	v_mul_hi_i32 v10, v9, s67
	v_ashrrev_i32_e32 v10, 4, v10
	v_mul_lo_u32 v11, v10, s52
	v_sub_u32_e32 v11, v9, v11
	v_lshl_add_u32 v12, v11, 3, s56
	v_cmp_lt_u32_e32 vcc, 63, v11
	s_nop 1
	v_cndmask_b32_e64 v13, 0, 1, vcc
	v_mad_u32_u24 v12, v13, v8, v12
	v_mul_u32_u24_e32 v65, 0x420, v10
	v_lshl_add_u32 v65, v11, 4, v65
	v_mul_u32_u24_e32 v9, 0x110, v10
	v_lshl_add_u32 v9, v11, 4, v9
	v_add_u32_e32 v9, 0x10400, v9
	v_cndmask_b32_e32 v65, v65, v9, vcc
	v_cmp_lt_u32_e32 vcc, 79, v11
	v_add_u32_e32 v9, 0x4300, v9
	s_nop 0
	v_cndmask_b32_e64 v13, 0, 1, vcc
	v_cndmask_b32_e32 v65, v65, v9, vcc
	v_lshl_add_u32 v12, v13, 7, v12
	v_mul_u32_u24_e32 v9, 0xc00, v10
	v_lshl_add_u32 v9, v12, 1, v9
	global_load_dwordx4 v[20:23], v9, s[12:13]
	v_add_u32_e32 v9, 1024, v142
	v_mul_hi_i32 v10, v9, s67
	v_ashrrev_i32_e32 v10, 4, v10
	v_mul_lo_u32 v11, v10, s52
	v_sub_u32_e32 v11, v9, v11
	v_lshl_add_u32 v12, v11, 3, s56
	v_cmp_lt_u32_e32 vcc, 63, v11
	s_nop 1
	v_cndmask_b32_e64 v13, 0, 1, vcc
	v_mad_u32_u24 v12, v13, v8, v12
	v_mul_u32_u24_e32 v66, 0x420, v10
	v_lshl_add_u32 v66, v11, 4, v66
	v_mul_u32_u24_e32 v9, 0x110, v10
	v_lshl_add_u32 v9, v11, 4, v9
	v_add_u32_e32 v9, 0x10400, v9
	v_cndmask_b32_e32 v66, v66, v9, vcc
	v_cmp_lt_u32_e32 vcc, 79, v11
	v_add_u32_e32 v9, 0x4300, v9
	s_nop 0
	v_cndmask_b32_e64 v13, 0, 1, vcc
	v_cndmask_b32_e32 v66, v66, v9, vcc
	v_lshl_add_u32 v12, v13, 7, v12
	v_mul_u32_u24_e32 v9, 0xc00, v10
	v_lshl_add_u32 v9, v12, 1, v9
	global_load_dwordx4 v[24:27], v9, s[12:13]
	v_add_u32_e32 v9, 1536, v142
	v_mul_hi_i32 v10, v9, s67
	v_ashrrev_i32_e32 v10, 4, v10
	v_mul_lo_u32 v11, v10, s52
	v_sub_u32_e32 v11, v9, v11
	v_lshl_add_u32 v12, v11, 3, s56
	v_cmp_lt_u32_e32 vcc, 63, v11
	s_nop 1
	v_cndmask_b32_e64 v13, 0, 1, vcc
	v_mad_u32_u24 v12, v13, v8, v12
	v_mul_u32_u24_e32 v67, 0x420, v10
	v_lshl_add_u32 v67, v11, 4, v67
	v_mul_u32_u24_e32 v9, 0x110, v10
	v_lshl_add_u32 v9, v11, 4, v9
	v_add_u32_e32 v9, 0x10400, v9
	v_cndmask_b32_e32 v67, v67, v9, vcc
	v_cmp_lt_u32_e32 vcc, 79, v11
	v_add_u32_e32 v9, 0x4300, v9
	s_nop 0
	v_cndmask_b32_e64 v13, 0, 1, vcc
	v_cndmask_b32_e32 v67, v67, v9, vcc
	v_lshl_add_u32 v12, v13, 7, v12
	v_mul_u32_u24_e32 v9, 0xc00, v10
	v_lshl_add_u32 v9, v12, 1, v9
	global_load_dwordx4 v[28:31], v9, s[12:13]
	v_add_u32_e32 v9, 2048, v142
	v_mul_hi_i32 v10, v9, s67
	v_ashrrev_i32_e32 v10, 4, v10
	v_mul_lo_u32 v11, v10, s52
	v_sub_u32_e32 v11, v9, v11
	v_lshl_add_u32 v12, v11, 3, s56
	v_cmp_lt_u32_e32 vcc, 63, v11
	s_nop 1
	v_cndmask_b32_e64 v13, 0, 1, vcc
	v_mad_u32_u24 v12, v13, v8, v12
	v_mul_u32_u24_e32 v68, 0x420, v10
	v_lshl_add_u32 v68, v11, 4, v68
	v_mul_u32_u24_e32 v9, 0x110, v10
	v_lshl_add_u32 v9, v11, 4, v9
	v_add_u32_e32 v9, 0x10400, v9
	v_cndmask_b32_e32 v68, v68, v9, vcc
	v_cmp_lt_u32_e32 vcc, 79, v11
	v_add_u32_e32 v9, 0x4300, v9
	s_nop 0
	v_cndmask_b32_e64 v13, 0, 1, vcc
	v_cndmask_b32_e32 v68, v68, v9, vcc
	v_lshl_add_u32 v12, v13, 7, v12
	v_mul_u32_u24_e32 v9, 0xc00, v10
	v_lshl_add_u32 v9, v12, 1, v9
	global_load_dwordx4 v[32:35], v9, s[12:13]
	v_add_u32_e32 v9, 2560, v142
	v_mul_hi_i32 v10, v9, s67
	v_ashrrev_i32_e32 v10, 4, v10
	v_mul_lo_u32 v11, v10, s52
	v_sub_u32_e32 v11, v9, v11
	v_lshl_add_u32 v12, v11, 3, s56
	v_cmp_lt_u32_e32 vcc, 63, v11
	s_nop 1
	v_cndmask_b32_e64 v13, 0, 1, vcc
	v_mad_u32_u24 v12, v13, v8, v12
	v_mul_u32_u24_e32 v69, 0x420, v10
	v_lshl_add_u32 v69, v11, 4, v69
	v_mul_u32_u24_e32 v9, 0x110, v10
	v_lshl_add_u32 v9, v11, 4, v9
	v_add_u32_e32 v9, 0x10400, v9
	v_cndmask_b32_e32 v69, v69, v9, vcc
	v_cmp_lt_u32_e32 vcc, 79, v11
	v_add_u32_e32 v9, 0x4300, v9
	s_nop 0
	v_cndmask_b32_e64 v13, 0, 1, vcc
	v_cndmask_b32_e32 v69, v69, v9, vcc
	v_lshl_add_u32 v12, v13, 7, v12
	v_mul_u32_u24_e32 v9, 0xc00, v10
	v_lshl_add_u32 v9, v12, 1, v9
	global_load_dwordx4 v[36:39], v9, s[12:13]
	v_add_u32_e32 v9, 3072, v142
	v_mul_hi_i32 v10, v9, s67
	v_ashrrev_i32_e32 v10, 4, v10
	v_mul_lo_u32 v11, v10, s52
	v_sub_u32_e32 v11, v9, v11
	v_lshl_add_u32 v12, v11, 3, s56
	v_cmp_lt_u32_e32 vcc, 63, v11
	s_nop 1
	v_cndmask_b32_e64 v13, 0, 1, vcc
	v_mad_u32_u24 v12, v13, v8, v12
	v_mul_u32_u24_e32 v70, 0x420, v10
	v_lshl_add_u32 v70, v11, 4, v70
	v_mul_u32_u24_e32 v9, 0x110, v10
	v_lshl_add_u32 v9, v11, 4, v9
	v_add_u32_e32 v9, 0x10400, v9
	v_cndmask_b32_e32 v70, v70, v9, vcc
	v_cmp_lt_u32_e32 vcc, 79, v11
	v_add_u32_e32 v9, 0x4300, v9
	s_nop 0
	v_cndmask_b32_e64 v13, 0, 1, vcc
	v_cndmask_b32_e32 v70, v70, v9, vcc
	v_lshl_add_u32 v12, v13, 7, v12
	v_mul_u32_u24_e32 v9, 0xc00, v10
	v_lshl_add_u32 v9, v12, 1, v9
	global_load_dwordx4 v[40:43], v9, s[12:13]
	v_add_u32_e32 v9, 3584, v142
	v_mul_hi_i32 v10, v9, s67
	v_ashrrev_i32_e32 v10, 4, v10
	v_mul_lo_u32 v11, v10, s52
	v_sub_u32_e32 v11, v9, v11
	v_lshl_add_u32 v12, v11, 3, s56
	v_cmp_lt_u32_e32 vcc, 63, v11
	s_nop 1
	v_cndmask_b32_e64 v13, 0, 1, vcc
	v_mad_u32_u24 v12, v13, v8, v12
	v_mul_u32_u24_e32 v71, 0x420, v10
	v_lshl_add_u32 v71, v11, 4, v71
	v_mul_u32_u24_e32 v9, 0x110, v10
	v_lshl_add_u32 v9, v11, 4, v9
	v_add_u32_e32 v9, 0x10400, v9
	v_cndmask_b32_e32 v71, v71, v9, vcc
	v_cmp_lt_u32_e32 vcc, 79, v11
	v_add_u32_e32 v9, 0x4300, v9
	s_nop 0
	v_cndmask_b32_e64 v13, 0, 1, vcc
	v_cndmask_b32_e32 v71, v71, v9, vcc
	v_lshl_add_u32 v12, v13, 7, v12
	v_mul_u32_u24_e32 v9, 0xc00, v10
	v_lshl_add_u32 v9, v12, 1, v9
	global_load_dwordx4 v[44:47], v9, s[12:13]
	v_add_u32_e32 v9, 4096, v142
	v_mul_hi_i32 v10, v9, s67
	v_ashrrev_i32_e32 v10, 4, v10
	v_mul_lo_u32 v11, v10, s52
	v_sub_u32_e32 v11, v9, v11
	v_lshl_add_u32 v12, v11, 3, s56
	v_cmp_lt_u32_e32 vcc, 63, v11
	s_nop 1
	v_cndmask_b32_e64 v13, 0, 1, vcc
	v_mad_u32_u24 v12, v13, v8, v12
	v_mul_u32_u24_e32 v72, 0x420, v10
	v_lshl_add_u32 v72, v11, 4, v72
	v_mul_u32_u24_e32 v9, 0x110, v10
	v_lshl_add_u32 v9, v11, 4, v9
	v_add_u32_e32 v9, 0x10400, v9
	v_cndmask_b32_e32 v72, v72, v9, vcc
	v_cmp_lt_u32_e32 vcc, 79, v11
	v_add_u32_e32 v9, 0x4300, v9
	s_nop 0
	v_cndmask_b32_e64 v13, 0, 1, vcc
	v_cndmask_b32_e32 v72, v72, v9, vcc
	v_lshl_add_u32 v12, v13, 7, v12
	v_mul_u32_u24_e32 v9, 0xc00, v10
	v_lshl_add_u32 v9, v12, 1, v9
	global_load_dwordx4 v[48:51], v9, s[12:13]
	v_add_u32_e32 v9, 4608, v142
	v_mul_hi_i32 v10, v9, s67
	v_ashrrev_i32_e32 v10, 4, v10
	v_mul_lo_u32 v11, v10, s52
	v_sub_u32_e32 v11, v9, v11
	v_lshl_add_u32 v12, v11, 3, s56
	v_cmp_lt_u32_e32 vcc, 63, v11
	s_nop 1
	v_cndmask_b32_e64 v13, 0, 1, vcc
	v_mad_u32_u24 v12, v13, v8, v12
	v_mul_u32_u24_e32 v73, 0x420, v10
	v_lshl_add_u32 v73, v11, 4, v73
	v_mul_u32_u24_e32 v9, 0x110, v10
	v_lshl_add_u32 v9, v11, 4, v9
	v_add_u32_e32 v9, 0x10400, v9
	v_cndmask_b32_e32 v73, v73, v9, vcc
	v_cmp_lt_u32_e32 vcc, 79, v11
	v_add_u32_e32 v9, 0x4300, v9
	s_nop 0
	v_cndmask_b32_e64 v13, 0, 1, vcc
	v_cndmask_b32_e32 v73, v73, v9, vcc
	v_lshl_add_u32 v12, v13, 7, v12
	v_mul_u32_u24_e32 v9, 0xc00, v10
	v_lshl_add_u32 v9, v12, 1, v9
	global_load_dwordx4 v[52:55], v9, s[12:13]
	v_add_u32_e32 v9, 5120, v142
	v_mul_hi_i32 v10, v9, s67
	v_ashrrev_i32_e32 v10, 4, v10
	v_mul_lo_u32 v11, v10, s52
	v_sub_u32_e32 v11, v9, v11
	v_lshl_add_u32 v12, v11, 3, s56
	v_cmp_lt_u32_e32 vcc, 63, v11
	s_nop 1
	v_cndmask_b32_e64 v13, 0, 1, vcc
	v_mad_u32_u24 v12, v13, v8, v12
	v_mul_u32_u24_e32 v74, 0x420, v10
	v_lshl_add_u32 v74, v11, 4, v74
	v_mul_u32_u24_e32 v9, 0x110, v10
	v_lshl_add_u32 v9, v11, 4, v9
	v_add_u32_e32 v9, 0x10400, v9
	v_cndmask_b32_e32 v74, v74, v9, vcc
	v_cmp_lt_u32_e32 vcc, 79, v11
	v_add_u32_e32 v9, 0x4300, v9
	s_nop 0
	v_cndmask_b32_e64 v13, 0, 1, vcc
	v_cndmask_b32_e32 v74, v74, v9, vcc
	v_lshl_add_u32 v12, v13, 7, v12
	v_mul_u32_u24_e32 v9, 0xc00, v10
	v_lshl_add_u32 v9, v12, 1, v9
	global_load_dwordx4 v[56:59], v9, s[12:13]
	v_add_u32_e32 v9, 5632, v142
	v_mul_hi_i32 v10, v9, s67
	v_ashrrev_i32_e32 v10, 4, v10
	v_mul_lo_u32 v11, v10, s52
	v_sub_u32_e32 v11, v9, v11
	v_lshl_add_u32 v12, v11, 3, s56
	v_cmp_lt_u32_e32 vcc, 63, v11
	s_nop 1
	v_cndmask_b32_e64 v13, 0, 1, vcc
	v_mad_u32_u24 v12, v13, v8, v12
	v_mul_u32_u24_e32 v75, 0x420, v10
	v_lshl_add_u32 v75, v11, 4, v75
	v_mul_u32_u24_e32 v9, 0x110, v10
	v_lshl_add_u32 v9, v11, 4, v9
	v_add_u32_e32 v9, 0x10400, v9
	v_cndmask_b32_e32 v75, v75, v9, vcc
	v_cmp_lt_u32_e32 vcc, 79, v11
	v_add_u32_e32 v9, 0x4300, v9
	s_nop 0
	v_cndmask_b32_e64 v13, 0, 1, vcc
	v_cndmask_b32_e32 v75, v75, v9, vcc
	v_lshl_add_u32 v12, v13, 7, v12
	v_mul_u32_u24_e32 v9, 0xc00, v10
	v_lshl_add_u32 v9, v12, 1, v9
	global_load_dwordx4 v[60:63], v9, s[12:13]
	s_waitcnt vmcnt(11)
	ds_write_b128 v64, v[16:19]
	s_waitcnt vmcnt(10)
	ds_write_b128 v65, v[20:23]
	s_waitcnt vmcnt(9)
	ds_write_b128 v66, v[24:27]
	s_waitcnt vmcnt(8)
	ds_write_b128 v67, v[28:31]
	s_waitcnt vmcnt(7)
	ds_write_b128 v68, v[32:35]
	s_waitcnt vmcnt(6)
	ds_write_b128 v69, v[36:39]
	s_waitcnt vmcnt(5)
	ds_write_b128 v70, v[40:43]
	s_waitcnt vmcnt(4)
	ds_write_b128 v71, v[44:47]
	s_waitcnt vmcnt(3)
	ds_write_b128 v72, v[48:51]
	s_waitcnt vmcnt(2)
	ds_write_b128 v73, v[52:55]
	s_waitcnt vmcnt(1)
	ds_write_b128 v74, v[56:59]
	s_waitcnt vmcnt(0)
	ds_write_b128 v75, v[60:63]
